# v13 + first modulated rmsnorm (phase A) row loops of chunks 0 and 1 software-prefetch the next row's 8 streamed f32 loads; bit-identical
# speedup vs baseline: 1.0075x; 1.0020x over previous
; __device__ __forceinline__ float bf_lo(unsigned w) { return __uint_as_float(w << 16); }
; __device__ __forceinline__ float bf_hi(unsigned w) { return __uint_as_float(w & 0xffff0000u); }
; __device__ __forceinline__ float wave_sum(float v) {
; #pragma unroll
;     for (int o = 1; o < 64; o <<= 1) v += __shfl_xor(v, o);
;     return v;
; template <bool MOD, bool SRC16>
; __device__ __forceinline__ void norm_rows(const float* src, int nrows, int tok0, const float* g, const float* ada, int sh_off, int sc_off, bf16* dst, float* dstf, int gw, int NGW, int lane_in) {
;     ...
;     for (int m = gw; m < nrows; m += NGW) {
;         f32x4 v[8]; float s = 0.f;
;         if (SRC16) { const v4u* xh = (const v4u*)((const bf16*)src + (size_t)m * 4096) + lane;
; #pragma unroll
;             for (int j = 0; j < 4; ++j) { const v4u w = xh[64 * j]; v[2 * j] = (f32x4){pg8::bf_lo(w.x), pg8::bf_hi(w.x), pg8::bf_lo(w.y), pg8::bf_hi(w.y)}; v[2 * j + 1] = (f32x4){pg8::bf_lo(w.z), pg8::bf_hi(w.z), pg8::bf_lo(w.w), pg8::bf_hi(w.w)}; } }
;         else { const f32x4* xr = (const f32x4*)(src + (size_t)m * DM) + lane;
; #pragma unroll
;             for (int j = 0; j < 8; ++j) v[j] = __builtin_nontemporal_load(xr + 64 * j); }
; #pragma unroll
;         for (int j = 0; j < 8; ++j) { s += (v[j].x * v[j].x + v[j].y * v[j].y) + (v[j].z * v[j].z + v[j].w * v[j].w); }
;         const float r = 1.0f / sqrtf(wave_sum(s) * (1.f / DM) + EPS);
;         if (MOD) {
;             const int b = batch_of(tok0 + m); const float* ab = ada + (size_t)b * ADAW;
;             f32x4 y[8];
; #pragma unroll
;             for (int j = 0; j < 8; ++j) { const int col = SRC16 ? 8 * (lane + 64 * (j >> 1)) + 4 * (j & 1) : 4 * (lane + 64 * j);
;                 const f32x4 gv = *(const f32x4*)(g + col), sc = *(const f32x4*)(ab + sc_off + col), sh = *(const f32x4*)(ab + sh_off + col);
.LBB0_129:
	s_or_b64 exec, exec, s[0:1]
	v_readlane_b32 s0, v248, 1
	s_mov_b32 s2, s91
	v_readlane_b32 s1, v248, 2
	s_mov_b32 s3, s67
	s_barrier
	v_mov_b32_e32 v0, v192
	v_readlane_b32 s2, v248, 39
	v_readlane_b32 s3, v248, 40
	s_cmpk_lt_i32 s2, 0x4000
	s_cselect_b64 s[2:3], -1, 0
	v_writelane_b32 v248, s2, 41
	s_and_b64 vcc, exec, s[2:3]
	s_nop 0
	v_writelane_b32 v248, s3, 42
	s_cbranch_vccz .LBB0_132
	v_mbcnt_hi_u32_b32 v2, -1, v152
	v_and_b32_e32 v3, 64, v2
	v_add_u32_e32 v3, 64, v3
	v_xor_b32_e32 v4, 1, v2
	v_cmp_lt_i32_e32 vcc, v4, v3
	s_add_u32 s2, s0, 0x100000
	v_readlane_b32 s4, v248, 39
	v_cndmask_b32_e32 v4, v2, v4, vcc
	v_lshlrev_b32_e32 v94, 2, v4
	v_xor_b32_e32 v4, 2, v2
	v_cmp_lt_i32_e32 vcc, v4, v3
	s_addc_u32 s3, s1, 0
	v_readlane_b32 s5, v248, 40
	v_cndmask_b32_e32 v4, v2, v4, vcc
	v_lshlrev_b32_e32 v95, 2, v4
	v_xor_b32_e32 v4, 4, v2
	v_cmp_lt_i32_e32 vcc, v4, v3
	s_mov_b32 s12, s4
	s_ashr_i32 s13, s4, 31
	v_cndmask_b32_e32 v4, v2, v4, vcc
	v_lshlrev_b32_e32 v96, 2, v4
	v_xor_b32_e32 v4, 8, v2
	v_cmp_lt_i32_e32 vcc, v4, v3
	s_lshl_b64 s[4:5], s[12:13], 13
	s_add_u32 s4, s48, s4
	v_cndmask_b32_e32 v4, v2, v4, vcc
	v_lshlrev_b32_e32 v97, 2, v4
	v_xor_b32_e32 v4, 16, v2
	v_cmp_lt_i32_e32 vcc, v4, v3
	v_ashrrev_i32_e32 v1, 31, v0
	s_addc_u32 s5, s49, s5
	v_cndmask_b32_e32 v4, v2, v4, vcc
	v_lshlrev_b32_e32 v98, 2, v4
	v_xor_b32_e32 v4, 32, v2
	v_lshl_add_u64 v[12:13], v[0:1], 4, s[4:5]
	s_mov_b64 s[4:5], 0x1000
	s_ashr_i32 s69, s68, 31
	v_cmp_lt_i32_e32 vcc, v4, v3
	v_lshl_add_u64 v[80:81], v[12:13], 0, s[4:5]
	s_lshl_b64 s[4:5], s[68:69], 13
	s_lshl_b64 s[6:7], s[12:13], 12
	v_cndmask_b32_e32 v2, v2, v4, vcc
	s_add_u32 s0, s0, s6
	v_lshlrev_b32_e32 v99, 2, v2
	v_lshlrev_b32_e32 v2, 2, v0
	s_addc_u32 s1, s1, s7
	v_add_u32_e32 v4, 0x400, v2
	v_add_u32_e32 v6, 0x500, v2
	v_add_u32_e32 v8, 0x600, v2
	v_add_u32_e32 v10, 0x700, v2
	v_lshl_add_u64 v[0:1], v[0:1], 3, s[0:1]
	s_mov_b64 s[0:1], 0x7a00000
	v_ashrrev_i32_e32 v3, 31, v2
	v_add_u32_e32 v66, 0x100, v2
	v_add_u32_e32 v68, 0x200, v2
	v_add_u32_e32 v70, 0x300, v2
	v_ashrrev_i32_e32 v5, 31, v4
	v_ashrrev_i32_e32 v7, 31, v6
	v_ashrrev_i32_e32 v9, 31, v8
	v_ashrrev_i32_e32 v11, 31, v10
	v_lshl_add_u64 v[82:83], v[0:1], 0, s[0:1]
	s_mov_b32 s0, s12
	v_lshl_add_u64 v[64:65], v[2:3], 2, s[60:61]
	v_ashrrev_i32_e32 v67, 31, v66
	v_ashrrev_i32_e32 v69, 31, v68
	v_ashrrev_i32_e32 v71, 31, v70
	v_lshl_add_u64 v[72:73], v[4:5], 2, s[60:61]
	v_lshl_add_u64 v[74:75], v[6:7], 2, s[60:61]
	v_lshl_add_u64 v[76:77], v[8:9], 2, s[60:61]
	v_lshl_add_u64 v[78:79], v[10:11], 2, s[60:61]
	s_lshl_b64 s[6:7], s[68:69], 12
	v_mov_b32_e32 v100, 0x358637bd
	s_mov_b32 s8, 0xf800000
	v_mov_b32_e32 v101, 0x260
	v_lshlrev_b64 v[84:85], 2, v[2:3]
	v_lshlrev_b64 v[86:87], 2, v[4:5]
	v_lshlrev_b64 v[88:89], 2, v[6:7]
	v_lshlrev_b64 v[90:91], 2, v[8:9]
	v_lshlrev_b64 v[92:93], 2, v[10:11]
	s_movk_i32 s9, 0x7fff
	s_mov_b32 s10, 0xffff0000
	v_writelane_b32 v248, s0, 39
	s_mov_b32 s11, s12
	s_nop 0
	v_writelane_b32 v248, s1, 40
	global_load_dwordx4 v[208:211], v[80:81], off offset:-4096 nt
	global_load_dwordx4 v[212:215], v[80:81], off offset:-3072 nt
	global_load_dwordx4 v[216:219], v[80:81], off offset:-2048 nt
	global_load_dwordx4 v[220:223], v[80:81], off nt
	global_load_dwordx4 v[224:227], v[80:81], off offset:-1024 nt
	global_load_dwordx4 v[228:231], v[80:81], off offset:1024 nt
	global_load_dwordx4 v[232:235], v[80:81], off offset:3072 nt
	global_load_dwordx4 v[236:239], v[80:81], off offset:2048 nt
.LBB0_131:
	s_ashr_i32 s0, s11, 12
	s_mul_hi_i32 s1, s0, 0xc000
	s_mul_i32 s0, s0, 0xc000
	s_add_u32 s0, s2, s0
	s_addc_u32 s1, s3, s1
	s_add_u32 s12, s0, 0x2000
	s_addc_u32 s13, s1, 0
	global_load_dwordx4 v[32:35], v[64:65], off
	global_load_dwordx4 v[36:39], v[64:65], off offset:1024
	global_load_dwordx4 v[40:43], v[64:65], off offset:2048
	global_load_dwordx4 v[44:47], v[64:65], off offset:3072
	global_load_dwordx4 v[48:51], v[72:73], off
	global_load_dwordx4 v[52:55], v[74:75], off
	global_load_dwordx4 v[56:59], v[76:77], off
	global_load_dwordx4 v[60:63], v[78:79], off
	v_lshl_add_u64 v[146:147], s[0:1], 0, v[84:85]
	v_lshl_add_u64 v[158:159], s[0:1], 0, v[88:89]
	v_lshl_add_u64 v[162:163], s[0:1], 0, v[90:91]
	v_lshl_add_u64 v[166:167], s[0:1], 0, v[92:93]
	v_lshl_add_u64 v[110:111], s[12:13], 0, v[84:85]
	v_lshl_add_u64 v[114:115], v[66:67], 2, s[12:13]
	v_lshl_add_u64 v[118:119], v[68:69], 2, s[12:13]
	v_lshl_add_u64 v[122:123], v[70:71], 2, s[12:13]
	v_lshl_add_u64 v[126:127], s[12:13], 0, v[86:87]
	v_lshl_add_u64 v[130:131], s[12:13], 0, v[88:89]
	v_lshl_add_u64 v[134:135], s[12:13], 0, v[90:91]
	v_lshl_add_u64 v[138:139], s[12:13], 0, v[92:93]
	v_lshl_add_u64 v[150:151], s[0:1], 0, v[86:87]
	flat_load_dwordx4 v[102:105], v[146:147] offset:1024
	flat_load_dwordx4 v[106:109], v[146:147] offset:2048
	s_nop 0
	flat_load_dwordx4 v[110:113], v[110:111]
	s_nop 0
	flat_load_dwordx4 v[114:117], v[114:115]
	s_nop 0
	flat_load_dwordx4 v[118:121], v[118:119]
	s_nop 0
	flat_load_dwordx4 v[122:125], v[122:123]
	s_nop 0
	flat_load_dwordx4 v[126:129], v[126:127]
	s_nop 0
	flat_load_dwordx4 v[130:133], v[130:131]
	s_nop 0
	flat_load_dwordx4 v[134:137], v[134:135]
	s_nop 0
	flat_load_dwordx4 v[138:141], v[138:139]
	s_nop 0
	flat_load_dwordx4 v[142:145], v[146:147]
	s_nop 0
	flat_load_dwordx4 v[146:149], v[146:147] offset:3072
	s_nop 0
	flat_load_dwordx4 v[154:157], v[150:151]
	s_nop 0
	flat_load_dwordx4 v[158:161], v[158:159]
	s_nop 0
	flat_load_dwordx4 v[162:165], v[162:163]
	s_nop 0
	flat_load_dwordx4 v[166:169], v[166:167]
	s_add_i32 s11, s11, s68
	v_lshl_add_u64 v[80:81], v[80:81], 0, s[4:5]
	s_cmpk_lt_i32 s11, 0x4000
	s_waitcnt vmcnt(0)
	v_mov_b64_e32 v[28:29], v[208:209]
	v_mov_b64_e32 v[30:31], v[210:211]
	v_mov_b64_e32 v[20:21], v[212:213]
	v_mov_b64_e32 v[22:23], v[214:215]
	v_mov_b64_e32 v[16:17], v[216:217]
	v_mov_b64_e32 v[18:19], v[218:219]
	v_mov_b64_e32 v[4:5], v[220:221]
	v_mov_b64_e32 v[6:7], v[222:223]
	v_mov_b64_e32 v[24:25], v[224:225]
	v_mov_b64_e32 v[26:27], v[226:227]
	v_mov_b64_e32 v[8:9], v[228:229]
	v_mov_b64_e32 v[10:11], v[230:231]
	v_mov_b64_e32 v[0:1], v[232:233]
	v_mov_b64_e32 v[2:3], v[234:235]
	v_mov_b64_e32 v[12:13], v[236:237]
	v_mov_b64_e32 v[14:15], v[238:239]
	s_cmpk_lt_i32 s11, 0x4000
	s_cbranch_scc0 .La_nopf_0
	global_load_dwordx4 v[208:211], v[80:81], off offset:-4096 nt
	global_load_dwordx4 v[212:215], v[80:81], off offset:-3072 nt
	global_load_dwordx4 v[216:219], v[80:81], off offset:-2048 nt
	global_load_dwordx4 v[220:223], v[80:81], off nt
	global_load_dwordx4 v[224:227], v[80:81], off offset:-1024 nt
	global_load_dwordx4 v[228:231], v[80:81], off offset:1024 nt
	global_load_dwordx4 v[232:235], v[80:81], off offset:3072 nt
	global_load_dwordx4 v[236:239], v[80:81], off offset:2048 nt
; __device__ __forceinline__ float wave_sum(float v) {
; #pragma unroll
;     for (int o = 1; o < 64; o <<= 1) v += __shfl_xor(v, o);
;     return v;
; }
; template <bool MOD, bool SRC16>
; __device__ __forceinline__ void norm_rows(const float* src, int nrows, int tok0, const float* g, const float* ada, int sh_off, int sc_off, bf16* dst, float* dstf, int gw, int NGW, int lane_in) {
;     ...
;         for (int j = 0; j < 8; ++j) { s += (v[j].x * v[j].x + v[j].y * v[j].y) + (v[j].z * v[j].z + v[j].w * v[j].w); }
;         const float r = 1.0f / sqrtf(wave_sum(s) * (1.f / DM) + EPS);
.La_nopf_0:
	v_mov_b32_e32 v170, v29
	v_mov_b32_e32 v171, v21
	v_mov_b32_e32 v174, v31
	v_mov_b32_e32 v175, v23
	v_mov_b32_e32 v150, v28
	v_mov_b32_e32 v151, v20
	v_mov_b32_e32 v172, v30
	v_mov_b32_e32 v173, v22
	v_pk_mul_f32 v[176:177], v[18:19], v[18:19]
	v_pk_mul_f32 v[178:179], v[16:17], v[16:17]
	v_pk_mul_f32 v[170:171], v[170:171], v[170:171]
	v_pk_mul_f32 v[174:175], v[174:175], v[174:175]
	v_pk_mov_b32 v[196:197], v[178:179], v[176:177] op_sel:[1,0]
	v_mov_b32_e32 v179, v177
	v_pk_fma_f32 v[150:151], v[150:151], v[150:151], v[170:171]
	v_pk_fma_f32 v[170:171], v[172:173], v[172:173], v[174:175]
	v_mul_f32_e32 v180, v25, v25
	v_mul_f32_e32 v182, v27, v27
	v_pk_add_f32 v[172:173], v[196:197], v[178:179]
	v_pk_add_f32 v[150:151], v[150:151], v[170:171]
	v_mul_f32_e32 v153, v4, v4
	v_mul_f32_e32 v191, v5, v5
	v_mul_f32_e32 v193, v6, v6
	v_mul_f32_e32 v195, v7, v7
	v_pk_fma_f32 v[176:177], v[24:25], v[24:25], v[180:181] op_sel_hi:[1,1,0]
	v_pk_fma_f32 v[180:181], v[26:27], v[26:27], v[182:183] op_sel_hi:[1,1,0]
	v_pk_add_f32 v[170:171], v[172:173], v[172:173] op_sel:[0,1] op_sel_hi:[1,0]
	v_pk_add_f32 v[150:151], v[150:151], v[150:151] op_sel:[0,1] op_sel_hi:[1,0]
	v_pk_mul_f32 v[184:185], v[10:11], v[10:11]
	v_pk_mul_f32 v[186:187], v[8:9], v[8:9]
	v_mov_b32_e32 v177, v193
	v_mov_b32_e32 v181, v195
	v_mov_b32_e32 v171, v191
	v_mov_b32_e32 v151, v153
	v_pk_mov_b32 v[182:183], v[186:187], v[184:185] op_sel:[1,0]
	v_mov_b32_e32 v187, v185
	v_pk_add_f32 v[172:173], v[176:177], v[180:181]
	v_pk_add_f32 v[150:151], v[150:151], v[170:171]
	v_mul_f32_e32 v188, v13, v13
	v_mul_f32_e32 v190, v15, v15
	v_pk_add_f32 v[174:175], v[182:183], v[186:187]
	v_pk_add_f32 v[150:151], v[150:151], v[172:173]
	v_mul_f32_e32 v198, v0, v0
	v_mul_f32_e32 v199, v1, v1
	v_mul_f32_e32 v200, v2, v2
	v_mul_f32_e32 v201, v3, v3
	v_pk_fma_f32 v[184:185], v[12:13], v[12:13], v[188:189] op_sel_hi:[1,1,0]
	v_pk_fma_f32 v[188:189], v[14:15], v[14:15], v[190:191] op_sel_hi:[1,1,0]
	v_pk_add_f32 v[174:175], v[174:175], v[174:175] op_sel:[0,1] op_sel_hi:[1,0]
	v_pk_add_f32 v[150:151], v[150:151], v[150:151] op_sel:[0,1] op_sel_hi:[1,0]
	v_mov_b32_e32 v185, v200
	v_mov_b32_e32 v189, v201
	v_mov_b32_e32 v175, v199
	v_mov_b32_e32 v151, v198
	v_pk_add_f32 v[176:177], v[184:185], v[188:189]
	v_pk_add_f32 v[150:151], v[150:151], v[174:175]
	s_waitcnt lgkmcnt(0)
	v_pk_add_f32 v[112:113], v[112:113], 1.0 op_sel_hi:[1,0]
	v_pk_add_f32 v[150:151], v[150:151], v[176:177]
	v_pk_add_f32 v[110:111], v[110:111], 1.0 op_sel_hi:[1,0]
	v_add_f32_e32 v150, v150, v151
	ds_bpermute_b32 v151, v94, v150
	v_pk_add_f32 v[116:117], v[116:117], 1.0 op_sel_hi:[1,0]
	v_pk_add_f32 v[114:115], v[114:115], 1.0 op_sel_hi:[1,0]
	v_pk_add_f32 v[120:121], v[120:121], 1.0 op_sel_hi:[1,0]
	v_pk_add_f32 v[118:119], v[118:119], 1.0 op_sel_hi:[1,0]
	s_waitcnt lgkmcnt(0)
	v_add_f32_e32 v150, v150, v151
	ds_bpermute_b32 v151, v95, v150
	v_pk_add_f32 v[124:125], v[124:125], 1.0 op_sel_hi:[1,0]
	v_pk_add_f32 v[122:123], v[122:123], 1.0 op_sel_hi:[1,0]
	v_pk_add_f32 v[128:129], v[128:129], 1.0 op_sel_hi:[1,0]
	v_pk_add_f32 v[126:127], v[126:127], 1.0 op_sel_hi:[1,0]
	s_waitcnt lgkmcnt(0)
	v_add_f32_e32 v150, v150, v151
	ds_bpermute_b32 v151, v96, v150
	v_pk_add_f32 v[132:133], v[132:133], 1.0 op_sel_hi:[1,0]
	v_pk_add_f32 v[130:131], v[130:131], 1.0 op_sel_hi:[1,0]
	v_pk_add_f32 v[136:137], v[136:137], 1.0 op_sel_hi:[1,0]
	v_pk_add_f32 v[134:135], v[134:135], 1.0 op_sel_hi:[1,0]
	s_waitcnt lgkmcnt(0)
	v_add_f32_e32 v150, v150, v151
	ds_bpermute_b32 v151, v97, v150
	v_pk_add_f32 v[140:141], v[140:141], 1.0 op_sel_hi:[1,0]
	v_pk_add_f32 v[138:139], v[138:139], 1.0 op_sel_hi:[1,0]
	s_waitcnt lgkmcnt(0)
	v_add_f32_e32 v150, v150, v151
	ds_bpermute_b32 v151, v98, v150
	s_waitcnt lgkmcnt(0)
	v_add_f32_e32 v150, v150, v151
	ds_bpermute_b32 v151, v99, v150
	s_waitcnt lgkmcnt(0)
; __device__ __forceinline__ unsigned pk2(float lo, float hi) { return f2bf(lo) | (f2bf(hi) << 16); }
; template <bool MOD, bool SRC16>
; __device__ __forceinline__ void norm_rows(const float* src, int nrows, int tok0, const float* g, const float* ada, int sh_off, int sc_off, bf16* dst, float* dstf, int gw, int NGW, int lane_in) {
;     ...
;         const float r = 1.0f / sqrtf(wave_sum(s) * (1.f / DM) + EPS);
;         if (MOD) {
;             const int b = batch_of(tok0 + m); const float* ab = ada + (size_t)b * ADAW;
;             f32x4 y[8];
; #pragma unroll
;             for (int j = 0; j < 8; ++j) { const int col = SRC16 ? 8 * (lane + 64 * (j >> 1)) + 4 * (j & 1) : 4 * (lane + 64 * j);
;                 const f32x4 gv = *(const f32x4*)(g + col), sc = *(const f32x4*)(ab + sc_off + col), sh = *(const f32x4*)(ab + sh_off + col);
;                 y[j] = (v[j] * r) * gv * (sc + 1.0f) + sh; }
;             if (SRC16) { v4u* o16 = (v4u*)(dst + (size_t)m * DM) + lane;
; #pragma unroll
;                 for (int j = 0; j < 4; ++j) { v4u w; w.x = pk2(y[2 * j].x, y[2 * j].y); w.y = pk2(y[2 * j].z, y[2 * j].w); w.z = pk2(y[2 * j + 1].x, y[2 * j + 1].y); w.w = pk2(y[2 * j + 1].z, y[2 * j + 1].w); o16[64 * j] = w; } }
;             else { v2u* o8 = (v2u*)(dst + (size_t)m * DM) + lane;
; #pragma unroll
;                 for (int j = 0; j < 8; ++j) { v2u w; w.x = pk2(y[j].x, y[j].y); w.y = pk2(y[j].z, y[j].w); o8[64 * j] = w; } }
	v_add_f32_e32 v150, v150, v151
	v_fmamk_f32 v150, v150, 0x3a000000, v100
	v_mul_f32_e32 v151, 0x4f800000, v150
	v_cmp_gt_f32_e32 vcc, s8, v150
	s_nop 1
	v_cndmask_b32_e32 v150, v150, v151, vcc
	v_sqrt_f32_e32 v151, v150
	s_nop 0
	v_add_u32_e32 v153, -1, v151
	v_add_u32_e32 v170, 1, v151
	v_fma_f32 v171, -v153, v151, v150
	v_fma_f32 v172, -v170, v151, v150
	v_cmp_ge_f32_e64 s[0:1], 0, v171
	s_nop 1
	v_cndmask_b32_e64 v151, v151, v153, s[0:1]
	v_cmp_lt_f32_e64 s[0:1], 0, v172
	s_nop 1
	v_cndmask_b32_e64 v151, v151, v170, s[0:1]
	v_mul_f32_e32 v153, 0x37800000, v151
	v_cndmask_b32_e32 v151, v151, v153, vcc
	v_cmp_class_f32_e32 vcc, v150, v101
	s_nop 1
	v_cndmask_b32_e32 v150, v151, v150, vcc
	v_div_scale_f32 v151, s[0:1], v150, v150, 1.0
	v_rcp_f32_e32 v170, v151
	v_div_scale_f32 v153, vcc, 1.0, v150, 1.0
	v_fma_f32 v171, -v151, v170, 1.0
	v_fmac_f32_e32 v170, v171, v170
	v_mul_f32_e32 v171, v153, v170
	v_fma_f32 v172, -v151, v171, v153
	v_fmac_f32_e32 v171, v172, v170
	v_fma_f32 v151, -v151, v171, v153
	v_div_fmas_f32 v151, v151, v170, v171
	v_div_fixup_f32 v150, v151, v150, 1.0
	v_pk_mul_f32 v[30:31], v[30:31], v[150:151] op_sel_hi:[1,0]
	v_pk_mul_f32 v[28:29], v[28:29], v[150:151] op_sel_hi:[1,0]
	v_pk_mul_f32 v[22:23], v[22:23], v[150:151] op_sel_hi:[1,0]
	v_pk_mul_f32 v[20:21], v[20:21], v[150:151] op_sel_hi:[1,0]
	v_pk_mul_f32 v[18:19], v[18:19], v[150:151] op_sel_hi:[1,0]
	v_pk_mul_f32 v[16:17], v[16:17], v[150:151] op_sel_hi:[1,0]
	v_pk_mul_f32 v[26:27], v[26:27], v[150:151] op_sel_hi:[1,0]
	v_pk_mul_f32 v[24:25], v[24:25], v[150:151] op_sel_hi:[1,0]
	v_pk_mul_f32 v[6:7], v[6:7], v[150:151] op_sel_hi:[1,0]
	v_pk_mul_f32 v[4:5], v[4:5], v[150:151] op_sel_hi:[1,0]
	v_pk_mul_f32 v[10:11], v[10:11], v[150:151] op_sel_hi:[1,0]
	v_pk_mul_f32 v[8:9], v[8:9], v[150:151] op_sel_hi:[1,0]
	v_pk_mul_f32 v[14:15], v[14:15], v[150:151] op_sel_hi:[1,0]
	v_pk_mul_f32 v[12:13], v[12:13], v[150:151] op_sel_hi:[1,0]
	v_pk_mul_f32 v[2:3], v[2:3], v[150:151] op_sel_hi:[1,0]
	v_pk_mul_f32 v[0:1], v[0:1], v[150:151] op_sel_hi:[1,0]
	v_pk_mul_f32 v[28:29], v[32:33], v[28:29]
	v_pk_mul_f32 v[30:31], v[34:35], v[30:31]
	v_pk_mul_f32 v[20:21], v[36:37], v[20:21]
	v_pk_mul_f32 v[22:23], v[38:39], v[22:23]
	v_pk_mul_f32 v[16:17], v[40:41], v[16:17]
	v_pk_mul_f32 v[18:19], v[42:43], v[18:19]
	v_pk_mul_f32 v[24:25], v[44:45], v[24:25]
	v_pk_mul_f32 v[26:27], v[46:47], v[26:27]
	v_pk_mul_f32 v[4:5], v[4:5], v[48:49]
	v_pk_mul_f32 v[6:7], v[6:7], v[50:51]
	v_pk_mul_f32 v[8:9], v[8:9], v[52:53]
	v_pk_mul_f32 v[10:11], v[10:11], v[54:55]
	v_pk_mul_f32 v[12:13], v[12:13], v[56:57]
	v_pk_mul_f32 v[14:15], v[14:15], v[58:59]
	v_pk_mul_f32 v[0:1], v[0:1], v[60:61]
	v_pk_mul_f32 v[2:3], v[2:3], v[62:63]
	v_pk_fma_f32 v[30:31], v[112:113], v[30:31], v[144:145]
	v_pk_fma_f32 v[28:29], v[110:111], v[28:29], v[142:143]
	v_pk_fma_f32 v[22:23], v[116:117], v[22:23], v[104:105]
	v_pk_fma_f32 v[20:21], v[114:115], v[20:21], v[102:103]
	v_pk_fma_f32 v[18:19], v[120:121], v[18:19], v[108:109]
	v_pk_fma_f32 v[16:17], v[118:119], v[16:17], v[106:107]
	v_pk_fma_f32 v[26:27], v[124:125], v[26:27], v[148:149]
	v_pk_fma_f32 v[24:25], v[122:123], v[24:25], v[146:147]
	v_pk_fma_f32 v[6:7], v[6:7], v[128:129], v[156:157]
	v_pk_fma_f32 v[4:5], v[4:5], v[126:127], v[154:155]
	v_pk_fma_f32 v[10:11], v[10:11], v[132:133], v[160:161]
	v_pk_fma_f32 v[8:9], v[8:9], v[130:131], v[158:159]
	v_pk_fma_f32 v[14:15], v[14:15], v[136:137], v[164:165]
	v_pk_fma_f32 v[12:13], v[12:13], v[134:135], v[162:163]
	v_pk_fma_f32 v[2:3], v[2:3], v[140:141], v[168:169]
	v_pk_fma_f32 v[0:1], v[0:1], v[138:139], v[166:167]
	v_bfe_u32 v32, v28, 16, 1
	v_bfe_u32 v34, v30, 16, 1
	v_bfe_u32 v33, v29, 16, 1
	v_bfe_u32 v35, v31, 16, 1
	v_bfe_u32 v36, v20, 16, 1
	v_bfe_u32 v38, v22, 16, 1
	v_bfe_u32 v40, v16, 16, 1
	v_bfe_u32 v42, v18, 16, 1
	v_bfe_u32 v44, v24, 16, 1
	v_bfe_u32 v46, v26, 16, 1
	v_bfe_u32 v48, v4, 16, 1
	v_bfe_u32 v49, v5, 16, 1
	v_bfe_u32 v50, v6, 16, 1
	v_bfe_u32 v51, v7, 16, 1
	v_bfe_u32 v52, v8, 16, 1
	v_bfe_u32 v53, v9, 16, 1
	v_bfe_u32 v54, v10, 16, 1
	v_bfe_u32 v56, v12, 16, 1
	v_bfe_u32 v57, v13, 16, 1
	v_bfe_u32 v58, v14, 16, 1
	v_bfe_u32 v59, v15, 16, 1
	v_bfe_u32 v60, v0, 16, 1
	v_bfe_u32 v61, v1, 16, 1
	v_bfe_u32 v62, v2, 16, 1
	v_bfe_u32 v63, v3, 16, 1
	v_add3_u32 v28, v28, v32, s9
	v_add3_u32 v30, v30, v34, s9
	v_bfe_u32 v37, v21, 16, 1
	v_bfe_u32 v39, v23, 16, 1
	v_bfe_u32 v41, v17, 16, 1
	v_bfe_u32 v43, v19, 16, 1
	v_bfe_u32 v45, v25, 16, 1
	v_bfe_u32 v47, v27, 16, 1
	v_bfe_u32 v55, v11, 16, 1
	v_add3_u32 v29, v29, v33, s9
	v_add3_u32 v31, v31, v35, s9
	v_add3_u32 v20, v20, v36, s9
	v_add3_u32 v22, v22, v38, s9
	v_add3_u32 v16, v16, v40, s9
	v_add3_u32 v18, v18, v42, s9
	v_add3_u32 v24, v24, v44, s9
	v_add3_u32 v26, v26, v46, s9
	v_add3_u32 v4, v4, v48, s9
	v_add3_u32 v32, v5, v49, s9
	v_add3_u32 v5, v6, v50, s9
	v_add3_u32 v33, v7, v51, s9
	v_add3_u32 v6, v8, v52, s9
	v_add3_u32 v34, v9, v53, s9
	v_add3_u32 v7, v10, v54, s9
	v_add3_u32 v8, v12, v56, s9
	v_add3_u32 v12, v13, v57, s9
	v_add3_u32 v9, v14, v58, s9
	v_add3_u32 v13, v15, v59, s9
	v_add3_u32 v0, v0, v60, s9
	v_add3_u32 v14, v1, v61, s9
	v_add3_u32 v1, v2, v62, s9
	v_add3_u32 v15, v3, v63, s9
	v_lshrrev_b32_e32 v2, 16, v28
	v_lshrrev_b32_e32 v3, 16, v30
	v_add3_u32 v21, v21, v37, s9
	v_add3_u32 v23, v23, v39, s9
	v_add3_u32 v17, v17, v41, s9
	v_add3_u32 v19, v19, v43, s9
	v_add3_u32 v25, v25, v45, s9
	v_add3_u32 v27, v27, v47, s9
	v_add3_u32 v11, v11, v55, s9
	v_lshrrev_b32_e32 v10, 16, v20
	v_lshrrev_b32_e32 v20, 16, v22
	v_lshrrev_b32_e32 v16, 16, v16
	v_lshrrev_b32_e32 v18, 16, v18
	v_lshrrev_b32_e32 v22, 16, v24
	v_lshrrev_b32_e32 v24, 16, v26
	v_lshrrev_b32_e32 v26, 16, v4
	v_lshrrev_b32_e32 v28, 16, v5
	v_lshrrev_b32_e32 v30, 16, v6
	v_lshrrev_b32_e32 v35, 16, v7
	v_lshrrev_b32_e32 v36, 16, v8
	v_lshrrev_b32_e32 v37, 16, v9
	v_lshrrev_b32_e32 v38, 16, v0
	v_lshrrev_b32_e32 v39, 16, v1
	v_and_or_b32 v0, v29, s10, v2
	v_and_or_b32 v1, v31, s10, v3
	v_and_or_b32 v2, v21, s10, v10
	v_and_or_b32 v3, v23, s10, v20
	v_and_or_b32 v4, v17, s10, v16
	v_and_or_b32 v5, v19, s10, v18
	v_and_or_b32 v6, v25, s10, v22
	v_and_or_b32 v7, v27, s10, v24
	v_and_or_b32 v8, v32, s10, v26
	v_and_or_b32 v9, v33, s10, v28
	v_and_or_b32 v10, v34, s10, v30
	v_and_or_b32 v11, v11, s10, v35
	v_and_or_b32 v12, v12, s10, v36
	v_and_or_b32 v13, v13, s10, v37
	v_and_or_b32 v14, v14, s10, v38
	v_and_or_b32 v15, v15, s10, v39
	flat_store_dwordx2 v[82:83], v[0:1]
	flat_store_dwordx2 v[82:83], v[2:3] offset:512
	flat_store_dwordx2 v[82:83], v[4:5] offset:1024
	flat_store_dwordx2 v[82:83], v[6:7] offset:1536
	flat_store_dwordx2 v[82:83], v[8:9] offset:2048
	flat_store_dwordx2 v[82:83], v[10:11] offset:2560
	flat_store_dwordx2 v[82:83], v[12:13] offset:3072
	flat_store_dwordx2 v[82:83], v[14:15] offset:3584
	v_lshl_add_u64 v[82:83], v[82:83], 0, s[6:7]
	s_cmpk_lt_i32 s11, 0x4000
	s_cbranch_scc1 .LBB0_131

; __device__ __forceinline__ float bf_lo(unsigned w) { return __uint_as_float(w << 16); }
; __device__ __forceinline__ float bf_hi(unsigned w) { return __uint_as_float(w & 0xffff0000u); }
; template <bool MOD, bool SRC16>
; __device__ __forceinline__ void norm_rows(const float* src, int nrows, int tok0, const float* g, const float* ada, int sh_off, int sc_off, bf16* dst, float* dstf, int gw, int NGW, int lane_in) {
;     ...
;     for (int m = gw; m < nrows; m += NGW) {
;         f32x4 v[8]; float s = 0.f;
;         if (SRC16) { const v4u* xh = (const v4u*)((const bf16*)src + (size_t)m * 4096) + lane;
; #pragma unroll
;             for (int j = 0; j < 4; ++j) { const v4u w = xh[64 * j]; v[2 * j] = (f32x4){pg8::bf_lo(w.x), pg8::bf_hi(w.x), pg8::bf_lo(w.y), pg8::bf_hi(w.y)}; v[2 * j + 1] = (f32x4){pg8::bf_lo(w.z), pg8::bf_hi(w.z), pg8::bf_lo(w.w), pg8::bf_hi(w.w)}; } }
;         else { const f32x4* xr = (const f32x4*)(src + (size_t)m * DM) + lane;
; #pragma unroll
;             for (int j = 0; j < 8; ++j) v[j] = __builtin_nontemporal_load(xr + 64 * j); }
; #pragma unroll
;         for (int j = 0; j < 8; ++j) { s += (v[j].x * v[j].x + v[j].y * v[j].y) + (v[j].z * v[j].z + v[j].w * v[j].w); }
;         const float r = 1.0f / sqrtf(wave_sum(s) * (1.f / DM) + EPS);
;         if (MOD) {
;             const int b = batch_of(tok0 + m); const float* ab = ada + (size_t)b * ADAW;
;             f32x4 y[8];
; #pragma unroll
;             for (int j = 0; j < 8; ++j) { const int col = SRC16 ? 8 * (lane + 64 * (j >> 1)) + 4 * (j & 1) : 4 * (lane + 64 * j);
;                 const f32x4 gv = *(const f32x4*)(g + col), sc = *(const f32x4*)(ab + sc_off + col), sh = *(const f32x4*)(ab + sh_off + col);
.LBB0_785:
	v_readlane_b32 s0, v248, 1
	s_mov_b32 s2, s91
	v_readlane_b32 s1, v248, 2
	s_mov_b32 s3, s64
	v_mov_b32_e32 v0, v192
	v_readlane_b32 s2, v248, 41
	v_readlane_b32 s3, v248, 42
	s_and_b64 vcc, exec, s[2:3]
	s_cbranch_vccz .LBB0_788
	s_add_u32 s2, s0, 0x100000
	v_readlane_b32 s4, v248, 39
	s_addc_u32 s3, s1, 0
	v_readlane_b32 s5, v248, 40
	s_mov_b32 s12, s4
	s_ashr_i32 s13, s4, 31
	s_lshl_b64 s[4:5], s[12:13], 13
	s_add_u32 s4, s50, s4
	v_ashrrev_i32_e32 v1, 31, v0
	s_addc_u32 s5, s51, s5
	v_lshl_add_u64 v[12:13], v[0:1], 4, s[4:5]
	s_mov_b64 s[4:5], 0x1000
	s_ashr_i32 s69, s68, 31
	v_lshl_add_u64 v[80:81], v[12:13], 0, s[4:5]
	s_lshl_b64 s[4:5], s[68:69], 13
	s_lshl_b64 s[6:7], s[12:13], 12
	s_add_u32 s0, s0, s6
	v_lshlrev_b32_e32 v2, 2, v0
	s_addc_u32 s1, s1, s7
	v_add_u32_e32 v4, 0x400, v2
	v_add_u32_e32 v6, 0x500, v2
	v_add_u32_e32 v8, 0x600, v2
	v_add_u32_e32 v10, 0x700, v2
	v_lshl_add_u64 v[0:1], v[0:1], 3, s[0:1]
	s_mov_b64 s[0:1], 0x7a00000
	v_ashrrev_i32_e32 v3, 31, v2
	v_add_u32_e32 v66, 0x100, v2
	v_add_u32_e32 v68, 0x200, v2
	v_add_u32_e32 v70, 0x300, v2
	v_ashrrev_i32_e32 v5, 31, v4
	v_ashrrev_i32_e32 v7, 31, v6
	v_ashrrev_i32_e32 v9, 31, v8
	v_ashrrev_i32_e32 v11, 31, v10
	v_lshl_add_u64 v[82:83], v[0:1], 0, s[0:1]
	s_mov_b32 s0, s12
	v_lshl_add_u64 v[64:65], v[2:3], 2, s[60:61]
	v_ashrrev_i32_e32 v67, 31, v66
	v_ashrrev_i32_e32 v69, 31, v68
	v_ashrrev_i32_e32 v71, 31, v70
	v_lshl_add_u64 v[72:73], v[4:5], 2, s[60:61]
	v_lshl_add_u64 v[74:75], v[6:7], 2, s[60:61]
	v_lshl_add_u64 v[76:77], v[8:9], 2, s[60:61]
	v_lshl_add_u64 v[78:79], v[10:11], 2, s[60:61]
	s_lshl_b64 s[6:7], s[68:69], 12
	v_mov_b32_e32 v94, 0x358637bd
	s_mov_b32 s8, 0xf800000
	v_mov_b32_e32 v95, 0x260
	v_lshlrev_b64 v[84:85], 2, v[2:3]
	v_lshlrev_b64 v[86:87], 2, v[4:5]
	v_lshlrev_b64 v[88:89], 2, v[6:7]
	v_lshlrev_b64 v[90:91], 2, v[8:9]
	v_lshlrev_b64 v[92:93], 2, v[10:11]
	s_movk_i32 s9, 0x7fff
	s_mov_b32 s10, 0xffff0000
	v_writelane_b32 v248, s0, 39
	s_mov_b32 s11, s12
	s_nop 0
	v_writelane_b32 v248, s1, 40
	global_load_dwordx4 v[208:211], v[80:81], off offset:-4096 nt
	global_load_dwordx4 v[212:215], v[80:81], off offset:-3072 nt
	global_load_dwordx4 v[216:219], v[80:81], off offset:-2048 nt
	global_load_dwordx4 v[220:223], v[80:81], off nt
	global_load_dwordx4 v[224:227], v[80:81], off offset:-1024 nt
	global_load_dwordx4 v[228:231], v[80:81], off offset:1024 nt
	global_load_dwordx4 v[232:235], v[80:81], off offset:2048 nt
	global_load_dwordx4 v[236:239], v[80:81], off offset:3072 nt
.LBB0_787:
	s_add_i32 s0, s11, 0x4000
	s_lshr_b32 s1, s11, 11
	s_ashr_i32 s0, s0, 12
	s_add_i32 s1, s1, 4
	s_cmp_lt_i32 s11, 0
	s_cselect_b32 s0, s0, s1
	s_mul_hi_i32 s1, s0, 0xc000
	s_mul_i32 s0, s0, 0xc000
	s_add_u32 s0, s2, s0
	s_addc_u32 s1, s3, s1
	s_add_u32 s12, s0, 0x2000
	s_addc_u32 s13, s1, 0
	global_load_dwordx4 v[32:35], v[64:65], off
	global_load_dwordx4 v[36:39], v[64:65], off offset:1024
	global_load_dwordx4 v[40:43], v[64:65], off offset:2048
	global_load_dwordx4 v[44:47], v[64:65], off offset:3072
	global_load_dwordx4 v[48:51], v[72:73], off
	global_load_dwordx4 v[52:55], v[74:75], off
	global_load_dwordx4 v[56:59], v[76:77], off
	global_load_dwordx4 v[60:63], v[78:79], off
	v_lshl_add_u64 v[140:141], s[0:1], 0, v[84:85]
	v_lshl_add_u64 v[144:145], s[0:1], 0, v[86:87]
	v_lshl_add_u64 v[148:149], s[0:1], 0, v[88:89]
	v_lshl_add_u64 v[152:153], s[0:1], 0, v[90:91]
	v_lshl_add_u64 v[156:157], s[0:1], 0, v[92:93]
	v_lshl_add_u64 v[104:105], s[12:13], 0, v[84:85]
	v_lshl_add_u64 v[108:109], v[66:67], 2, s[12:13]
	v_lshl_add_u64 v[112:113], v[68:69], 2, s[12:13]
	v_lshl_add_u64 v[116:117], v[70:71], 2, s[12:13]
	v_lshl_add_u64 v[120:121], s[12:13], 0, v[86:87]
	v_lshl_add_u64 v[124:125], s[12:13], 0, v[88:89]
	v_lshl_add_u64 v[128:129], s[12:13], 0, v[90:91]
	v_lshl_add_u64 v[132:133], s[12:13], 0, v[92:93]
	flat_load_dwordx4 v[96:99], v[140:141] offset:1024
	flat_load_dwordx4 v[100:103], v[140:141] offset:2048
	s_nop 0
	flat_load_dwordx4 v[104:107], v[104:105]
	s_nop 0
	flat_load_dwordx4 v[108:111], v[108:109]
	s_nop 0
	flat_load_dwordx4 v[112:115], v[112:113]
	s_nop 0
	flat_load_dwordx4 v[116:119], v[116:117]
	s_nop 0
	flat_load_dwordx4 v[120:123], v[120:121]
	s_nop 0
	flat_load_dwordx4 v[124:127], v[124:125]
	s_nop 0
	flat_load_dwordx4 v[128:131], v[128:129]
	s_nop 0
	flat_load_dwordx4 v[132:135], v[132:133]
	s_nop 0
	flat_load_dwordx4 v[136:139], v[140:141]
	s_nop 0
	flat_load_dwordx4 v[140:143], v[140:141] offset:3072
	s_nop 0
	flat_load_dwordx4 v[144:147], v[144:145]
	s_nop 0
	flat_load_dwordx4 v[148:151], v[148:149]
	s_nop 0
	flat_load_dwordx4 v[152:155], v[152:153]
	s_nop 0
	flat_load_dwordx4 v[156:159], v[156:157]
	s_add_i32 s11, s11, s68
	v_lshl_add_u64 v[80:81], v[80:81], 0, s[4:5]
	s_cmpk_lt_i32 s11, 0x4000
	s_waitcnt vmcnt(0)
	v_mov_b64_e32 v[28:29], v[208:209]
	v_mov_b64_e32 v[30:31], v[210:211]
	v_mov_b64_e32 v[20:21], v[212:213]
	v_mov_b64_e32 v[22:23], v[214:215]
	v_mov_b64_e32 v[16:17], v[216:217]
	v_mov_b64_e32 v[18:19], v[218:219]
	v_mov_b64_e32 v[8:9], v[220:221]
	v_mov_b64_e32 v[10:11], v[222:223]
	v_mov_b64_e32 v[24:25], v[224:225]
	v_mov_b64_e32 v[26:27], v[226:227]
	v_mov_b64_e32 v[12:13], v[228:229]
	v_mov_b64_e32 v[14:15], v[230:231]
	v_mov_b64_e32 v[4:5], v[232:233]
	v_mov_b64_e32 v[6:7], v[234:235]
	v_mov_b64_e32 v[0:1], v[236:237]
	v_mov_b64_e32 v[2:3], v[238:239]
	s_cmpk_lt_i32 s11, 0x4000
	s_cbranch_scc0 .La_nopf_1
	global_load_dwordx4 v[208:211], v[80:81], off offset:-4096 nt
	global_load_dwordx4 v[212:215], v[80:81], off offset:-3072 nt
	global_load_dwordx4 v[216:219], v[80:81], off offset:-2048 nt
	global_load_dwordx4 v[220:223], v[80:81], off nt
	global_load_dwordx4 v[224:227], v[80:81], off offset:-1024 nt
	global_load_dwordx4 v[228:231], v[80:81], off offset:1024 nt
	global_load_dwordx4 v[232:235], v[80:81], off offset:2048 nt
	global_load_dwordx4 v[236:239], v[80:81], off offset:3072 nt
; __device__ __forceinline__ float wave_sum(float v) {
; #pragma unroll
;     for (int o = 1; o < 64; o <<= 1) v += __shfl_xor(v, o);
;     return v;
; }
; template <bool MOD, bool SRC16>
; __device__ __forceinline__ void norm_rows(const float* src, int nrows, int tok0, const float* g, const float* ada, int sh_off, int sc_off, bf16* dst, float* dstf, int gw, int NGW, int lane_in) {
;     ...
;         for (int j = 0; j < 8; ++j) { s += (v[j].x * v[j].x + v[j].y * v[j].y) + (v[j].z * v[j].z + v[j].w * v[j].w); }
;         const float r = 1.0f / sqrtf(wave_sum(s) * (1.f / DM) + EPS);
.La_nopf_1:
	v_mov_b32_e32 v162, v29
	v_mov_b32_e32 v163, v21
	v_mov_b32_e32 v166, v31
	v_mov_b32_e32 v167, v23
	v_mov_b32_e32 v160, v28
	v_mov_b32_e32 v161, v20
	v_mov_b32_e32 v164, v30
	v_mov_b32_e32 v165, v22
	v_pk_mul_f32 v[168:169], v[18:19], v[18:19]
	v_pk_mul_f32 v[170:171], v[16:17], v[16:17]
	v_pk_mul_f32 v[162:163], v[162:163], v[162:163]
	v_pk_mul_f32 v[166:167], v[166:167], v[166:167]
	v_pk_mov_b32 v[184:185], v[170:171], v[168:169] op_sel:[1,0]
	v_mov_b32_e32 v171, v169
	v_pk_fma_f32 v[160:161], v[160:161], v[160:161], v[162:163]
	v_pk_fma_f32 v[162:163], v[164:165], v[164:165], v[166:167]
	v_mul_f32_e32 v172, v25, v25
	v_mul_f32_e32 v174, v27, v27
	v_pk_add_f32 v[164:165], v[184:185], v[170:171]
	v_pk_add_f32 v[160:161], v[160:161], v[162:163]
	v_mul_f32_e32 v183, v8, v8
	v_mul_f32_e32 v186, v9, v9
	v_mul_f32_e32 v187, v10, v10
	v_mul_f32_e32 v188, v11, v11
	v_pk_fma_f32 v[168:169], v[24:25], v[24:25], v[172:173] op_sel_hi:[1,1,0]
	v_pk_fma_f32 v[172:173], v[26:27], v[26:27], v[174:175] op_sel_hi:[1,1,0]
	v_pk_add_f32 v[162:163], v[164:165], v[164:165] op_sel:[0,1] op_sel_hi:[1,0]
	v_pk_add_f32 v[160:161], v[160:161], v[160:161] op_sel:[0,1] op_sel_hi:[1,0]
	v_pk_mul_f32 v[176:177], v[14:15], v[14:15]
	v_pk_mul_f32 v[178:179], v[12:13], v[12:13]
	v_mov_b32_e32 v169, v187
	v_mov_b32_e32 v173, v188
	v_mov_b32_e32 v163, v186
	v_mov_b32_e32 v161, v183
	v_pk_mov_b32 v[174:175], v[178:179], v[176:177] op_sel:[1,0]
	v_mov_b32_e32 v179, v177
	v_pk_add_f32 v[164:165], v[168:169], v[172:173]
	v_pk_add_f32 v[160:161], v[160:161], v[162:163]
	v_mul_f32_e32 v180, v5, v5
	v_mul_f32_e32 v182, v7, v7
	v_pk_add_f32 v[166:167], v[174:175], v[178:179]
	v_pk_add_f32 v[160:161], v[160:161], v[164:165]
	v_mul_f32_e32 v189, v0, v0
	v_mul_f32_e32 v190, v1, v1
	v_mul_f32_e32 v191, v2, v2
	v_mul_f32_e32 v193, v3, v3
	v_pk_fma_f32 v[176:177], v[4:5], v[4:5], v[180:181] op_sel_hi:[1,1,0]
	v_pk_fma_f32 v[180:181], v[6:7], v[6:7], v[182:183] op_sel_hi:[1,1,0]
	v_pk_add_f32 v[166:167], v[166:167], v[166:167] op_sel:[0,1] op_sel_hi:[1,0]
	v_pk_add_f32 v[160:161], v[160:161], v[160:161] op_sel:[0,1] op_sel_hi:[1,0]
	v_mov_b32_e32 v177, v191
	v_mov_b32_e32 v181, v193
	v_mov_b32_e32 v167, v190
	v_mov_b32_e32 v161, v189
	v_pk_add_f32 v[168:169], v[176:177], v[180:181]
	v_pk_add_f32 v[160:161], v[160:161], v[166:167]
	s_waitcnt lgkmcnt(0)
	v_pk_add_f32 v[106:107], v[106:107], 1.0 op_sel_hi:[1,0]
	v_pk_add_f32 v[160:161], v[160:161], v[168:169]
	v_pk_add_f32 v[104:105], v[104:105], 1.0 op_sel_hi:[1,0]
	v_add_f32_e32 v160, v160, v161
	ds_bpermute_b32 v161, v195, v160
	v_pk_add_f32 v[110:111], v[110:111], 1.0 op_sel_hi:[1,0]
	v_pk_add_f32 v[108:109], v[108:109], 1.0 op_sel_hi:[1,0]
	v_pk_add_f32 v[114:115], v[114:115], 1.0 op_sel_hi:[1,0]
	v_pk_add_f32 v[112:113], v[112:113], 1.0 op_sel_hi:[1,0]
	s_waitcnt lgkmcnt(0)
	v_add_f32_e32 v160, v160, v161
	ds_bpermute_b32 v161, v202, v160
	v_pk_add_f32 v[118:119], v[118:119], 1.0 op_sel_hi:[1,0]
	v_pk_add_f32 v[116:117], v[116:117], 1.0 op_sel_hi:[1,0]
	v_pk_add_f32 v[122:123], v[122:123], 1.0 op_sel_hi:[1,0]
	v_pk_add_f32 v[120:121], v[120:121], 1.0 op_sel_hi:[1,0]
	s_waitcnt lgkmcnt(0)
	v_add_f32_e32 v160, v160, v161
	ds_bpermute_b32 v161, v203, v160
	v_pk_add_f32 v[126:127], v[126:127], 1.0 op_sel_hi:[1,0]
	v_pk_add_f32 v[124:125], v[124:125], 1.0 op_sel_hi:[1,0]
	v_pk_add_f32 v[130:131], v[130:131], 1.0 op_sel_hi:[1,0]
	v_pk_add_f32 v[128:129], v[128:129], 1.0 op_sel_hi:[1,0]
	s_waitcnt lgkmcnt(0)
	v_add_f32_e32 v160, v160, v161
	ds_bpermute_b32 v161, v204, v160
	v_pk_add_f32 v[134:135], v[134:135], 1.0 op_sel_hi:[1,0]
	v_pk_add_f32 v[132:133], v[132:133], 1.0 op_sel_hi:[1,0]
	s_waitcnt lgkmcnt(0)
	v_add_f32_e32 v160, v160, v161
	ds_bpermute_b32 v161, v205, v160
	s_waitcnt lgkmcnt(0)
	v_add_f32_e32 v160, v160, v161
	ds_bpermute_b32 v161, v206, v160
	s_waitcnt lgkmcnt(0)
; __device__ __forceinline__ unsigned pk2(float lo, float hi) { return f2bf(lo) | (f2bf(hi) << 16); }
; template <bool MOD, bool SRC16>
; __device__ __forceinline__ void norm_rows(const float* src, int nrows, int tok0, const float* g, const float* ada, int sh_off, int sc_off, bf16* dst, float* dstf, int gw, int NGW, int lane_in) {
;     ...
;         const float r = 1.0f / sqrtf(wave_sum(s) * (1.f / DM) + EPS);
;         if (MOD) {
;             const int b = batch_of(tok0 + m); const float* ab = ada + (size_t)b * ADAW;
;             f32x4 y[8];
; #pragma unroll
;             for (int j = 0; j < 8; ++j) { const int col = SRC16 ? 8 * (lane + 64 * (j >> 1)) + 4 * (j & 1) : 4 * (lane + 64 * j);
;                 const f32x4 gv = *(const f32x4*)(g + col), sc = *(const f32x4*)(ab + sc_off + col), sh = *(const f32x4*)(ab + sh_off + col);
;                 y[j] = (v[j] * r) * gv * (sc + 1.0f) + sh; }
;             if (SRC16) { v4u* o16 = (v4u*)(dst + (size_t)m * DM) + lane;
; #pragma unroll
;                 for (int j = 0; j < 4; ++j) { v4u w; w.x = pk2(y[2 * j].x, y[2 * j].y); w.y = pk2(y[2 * j].z, y[2 * j].w); w.z = pk2(y[2 * j + 1].x, y[2 * j + 1].y); w.w = pk2(y[2 * j + 1].z, y[2 * j + 1].w); o16[64 * j] = w; } }
;             else { v2u* o8 = (v2u*)(dst + (size_t)m * DM) + lane;
; #pragma unroll
;                 for (int j = 0; j < 8; ++j) { v2u w; w.x = pk2(y[j].x, y[j].y); w.y = pk2(y[j].z, y[j].w); o8[64 * j] = w; } }
	v_add_f32_e32 v160, v160, v161
	v_fmamk_f32 v160, v160, 0x3a000000, v94
	v_mul_f32_e32 v161, 0x4f800000, v160
	v_cmp_gt_f32_e32 vcc, s8, v160
	s_nop 1
	v_cndmask_b32_e32 v160, v160, v161, vcc
	v_sqrt_f32_e32 v161, v160
	s_nop 0
	v_add_u32_e32 v162, -1, v161
	v_add_u32_e32 v163, 1, v161
	v_fma_f32 v164, -v162, v161, v160
	v_fma_f32 v165, -v163, v161, v160
	v_cmp_ge_f32_e64 s[0:1], 0, v164
	s_nop 1
	v_cndmask_b32_e64 v161, v161, v162, s[0:1]
	v_cmp_lt_f32_e64 s[0:1], 0, v165
	s_nop 1
	v_cndmask_b32_e64 v161, v161, v163, s[0:1]
	v_mul_f32_e32 v162, 0x37800000, v161
	v_cndmask_b32_e32 v161, v161, v162, vcc
	v_cmp_class_f32_e32 vcc, v160, v95
	s_nop 1
	v_cndmask_b32_e32 v160, v161, v160, vcc
	v_div_scale_f32 v161, s[0:1], v160, v160, 1.0
	v_rcp_f32_e32 v163, v161
	v_div_scale_f32 v162, vcc, 1.0, v160, 1.0
	v_fma_f32 v164, -v161, v163, 1.0
	v_fmac_f32_e32 v163, v164, v163
	v_mul_f32_e32 v164, v162, v163
	v_fma_f32 v165, -v161, v164, v162
	v_fmac_f32_e32 v164, v165, v163
	v_fma_f32 v161, -v161, v164, v162
	v_div_fmas_f32 v161, v161, v163, v164
	v_div_fixup_f32 v160, v161, v160, 1.0
	v_pk_mul_f32 v[30:31], v[30:31], v[160:161] op_sel_hi:[1,0]
	v_pk_mul_f32 v[28:29], v[28:29], v[160:161] op_sel_hi:[1,0]
	v_pk_mul_f32 v[22:23], v[22:23], v[160:161] op_sel_hi:[1,0]
	v_pk_mul_f32 v[20:21], v[20:21], v[160:161] op_sel_hi:[1,0]
	v_pk_mul_f32 v[18:19], v[18:19], v[160:161] op_sel_hi:[1,0]
	v_pk_mul_f32 v[16:17], v[16:17], v[160:161] op_sel_hi:[1,0]
	v_pk_mul_f32 v[26:27], v[26:27], v[160:161] op_sel_hi:[1,0]
	v_pk_mul_f32 v[24:25], v[24:25], v[160:161] op_sel_hi:[1,0]
	v_pk_mul_f32 v[10:11], v[10:11], v[160:161] op_sel_hi:[1,0]
	v_pk_mul_f32 v[8:9], v[8:9], v[160:161] op_sel_hi:[1,0]
	v_pk_mul_f32 v[14:15], v[14:15], v[160:161] op_sel_hi:[1,0]
	v_pk_mul_f32 v[12:13], v[12:13], v[160:161] op_sel_hi:[1,0]
	v_pk_mul_f32 v[6:7], v[6:7], v[160:161] op_sel_hi:[1,0]
	v_pk_mul_f32 v[4:5], v[4:5], v[160:161] op_sel_hi:[1,0]
	v_pk_mul_f32 v[2:3], v[2:3], v[160:161] op_sel_hi:[1,0]
	v_pk_mul_f32 v[0:1], v[0:1], v[160:161] op_sel_hi:[1,0]
	v_pk_mul_f32 v[28:29], v[32:33], v[28:29]
	v_pk_mul_f32 v[30:31], v[34:35], v[30:31]
	v_pk_mul_f32 v[20:21], v[36:37], v[20:21]
	v_pk_mul_f32 v[22:23], v[38:39], v[22:23]
	v_pk_mul_f32 v[16:17], v[40:41], v[16:17]
	v_pk_mul_f32 v[18:19], v[42:43], v[18:19]
	v_pk_mul_f32 v[24:25], v[44:45], v[24:25]
	v_pk_mul_f32 v[26:27], v[46:47], v[26:27]
	v_pk_mul_f32 v[8:9], v[8:9], v[48:49]
	v_pk_mul_f32 v[10:11], v[10:11], v[50:51]
	v_pk_mul_f32 v[12:13], v[12:13], v[52:53]
	v_pk_mul_f32 v[14:15], v[14:15], v[54:55]
	v_pk_mul_f32 v[4:5], v[4:5], v[56:57]
	v_pk_mul_f32 v[6:7], v[6:7], v[58:59]
	v_pk_mul_f32 v[0:1], v[0:1], v[60:61]
	v_pk_mul_f32 v[2:3], v[2:3], v[62:63]
	v_pk_fma_f32 v[30:31], v[106:107], v[30:31], v[138:139]
	v_pk_fma_f32 v[28:29], v[104:105], v[28:29], v[136:137]
	v_pk_fma_f32 v[22:23], v[110:111], v[22:23], v[98:99]
	v_pk_fma_f32 v[20:21], v[108:109], v[20:21], v[96:97]
	v_pk_fma_f32 v[18:19], v[114:115], v[18:19], v[102:103]
	v_pk_fma_f32 v[16:17], v[112:113], v[16:17], v[100:101]
	v_pk_fma_f32 v[26:27], v[118:119], v[26:27], v[142:143]
	v_pk_fma_f32 v[24:25], v[116:117], v[24:25], v[140:141]
	v_pk_fma_f32 v[10:11], v[10:11], v[122:123], v[146:147]
	v_pk_fma_f32 v[8:9], v[8:9], v[120:121], v[144:145]
	v_pk_fma_f32 v[14:15], v[14:15], v[126:127], v[150:151]
	v_pk_fma_f32 v[12:13], v[12:13], v[124:125], v[148:149]
	v_pk_fma_f32 v[6:7], v[6:7], v[130:131], v[154:155]
	v_pk_fma_f32 v[4:5], v[4:5], v[128:129], v[152:153]
	v_pk_fma_f32 v[2:3], v[2:3], v[134:135], v[158:159]
	v_pk_fma_f32 v[0:1], v[0:1], v[132:133], v[156:157]
	v_bfe_u32 v32, v28, 16, 1
	v_bfe_u32 v34, v30, 16, 1
	v_bfe_u32 v33, v29, 16, 1
	v_bfe_u32 v35, v31, 16, 1
	v_bfe_u32 v36, v20, 16, 1
	v_bfe_u32 v38, v22, 16, 1
	v_bfe_u32 v40, v16, 16, 1
	v_bfe_u32 v42, v18, 16, 1
	v_bfe_u32 v44, v24, 16, 1
	v_bfe_u32 v46, v26, 16, 1
	v_bfe_u32 v48, v8, 16, 1
	v_bfe_u32 v50, v10, 16, 1
	v_bfe_u32 v52, v12, 16, 1
	v_bfe_u32 v54, v14, 16, 1
	v_bfe_u32 v56, v4, 16, 1
	v_bfe_u32 v57, v5, 16, 1
	v_bfe_u32 v58, v6, 16, 1
	v_bfe_u32 v60, v0, 16, 1
	v_bfe_u32 v61, v1, 16, 1
	v_bfe_u32 v62, v2, 16, 1
	v_bfe_u32 v63, v3, 16, 1
	v_add3_u32 v28, v28, v32, s9
	v_add3_u32 v30, v30, v34, s9
	v_bfe_u32 v37, v21, 16, 1
	v_bfe_u32 v39, v23, 16, 1
	v_bfe_u32 v41, v17, 16, 1
	v_bfe_u32 v43, v19, 16, 1
	v_bfe_u32 v45, v25, 16, 1
	v_bfe_u32 v47, v27, 16, 1
	v_bfe_u32 v49, v9, 16, 1
	v_bfe_u32 v51, v11, 16, 1
	v_bfe_u32 v53, v13, 16, 1
	v_bfe_u32 v55, v15, 16, 1
	v_bfe_u32 v59, v7, 16, 1
	v_add3_u32 v29, v29, v33, s9
	v_add3_u32 v31, v31, v35, s9
	v_add3_u32 v20, v20, v36, s9
	v_add3_u32 v22, v22, v38, s9
	v_add3_u32 v16, v16, v40, s9
	v_add3_u32 v18, v18, v42, s9
	v_add3_u32 v24, v24, v44, s9
	v_add3_u32 v26, v26, v46, s9
	v_add3_u32 v8, v8, v48, s9
	v_add3_u32 v10, v10, v50, s9
	v_add3_u32 v12, v12, v52, s9
	v_add3_u32 v14, v14, v54, s9
	v_add3_u32 v4, v4, v56, s9
	v_add3_u32 v32, v5, v57, s9
	v_add3_u32 v5, v6, v58, s9
	v_add3_u32 v0, v0, v60, s9
	v_add3_u32 v34, v1, v61, s9
	v_add3_u32 v1, v2, v62, s9
	v_add3_u32 v35, v3, v63, s9
	v_lshrrev_b32_e32 v2, 16, v28
	v_lshrrev_b32_e32 v3, 16, v30
	v_add3_u32 v21, v21, v37, s9
	v_add3_u32 v23, v23, v39, s9
	v_add3_u32 v17, v17, v41, s9
	v_add3_u32 v19, v19, v43, s9
	v_add3_u32 v25, v25, v45, s9
	v_add3_u32 v27, v27, v47, s9
	v_add3_u32 v9, v9, v49, s9
	v_add3_u32 v11, v11, v51, s9
	v_add3_u32 v13, v13, v53, s9
	v_add3_u32 v15, v15, v55, s9
	v_add3_u32 v33, v7, v59, s9
	v_lshrrev_b32_e32 v6, 16, v20
	v_lshrrev_b32_e32 v7, 16, v22
	v_lshrrev_b32_e32 v16, 16, v16
	v_lshrrev_b32_e32 v18, 16, v18
	v_lshrrev_b32_e32 v20, 16, v24
	v_lshrrev_b32_e32 v22, 16, v26
	v_lshrrev_b32_e32 v8, 16, v8
	v_lshrrev_b32_e32 v10, 16, v10
	v_lshrrev_b32_e32 v12, 16, v12
	v_lshrrev_b32_e32 v14, 16, v14
	v_lshrrev_b32_e32 v24, 16, v4
	v_lshrrev_b32_e32 v26, 16, v5
	v_lshrrev_b32_e32 v28, 16, v0
	v_lshrrev_b32_e32 v30, 16, v1
	v_and_or_b32 v0, v29, s10, v2
	v_and_or_b32 v1, v31, s10, v3
	v_and_or_b32 v2, v21, s10, v6
	v_and_or_b32 v3, v23, s10, v7
	v_and_or_b32 v4, v17, s10, v16
	v_and_or_b32 v5, v19, s10, v18
	v_and_or_b32 v6, v25, s10, v20
	v_and_or_b32 v7, v27, s10, v22
	v_and_or_b32 v8, v9, s10, v8
	v_and_or_b32 v9, v11, s10, v10
	v_and_or_b32 v10, v13, s10, v12
	v_and_or_b32 v11, v15, s10, v14
	v_and_or_b32 v12, v32, s10, v24
	v_and_or_b32 v13, v33, s10, v26
	v_and_or_b32 v14, v34, s10, v28
	v_and_or_b32 v15, v35, s10, v30
	flat_store_dwordx2 v[82:83], v[0:1]
	flat_store_dwordx2 v[82:83], v[2:3] offset:512
	flat_store_dwordx2 v[82:83], v[4:5] offset:1024
	flat_store_dwordx2 v[82:83], v[6:7] offset:1536
	flat_store_dwordx2 v[82:83], v[8:9] offset:2048
	flat_store_dwordx2 v[82:83], v[10:11] offset:2560
	flat_store_dwordx2 v[82:83], v[12:13] offset:3072
	flat_store_dwordx2 v[82:83], v[14:15] offset:3584
	v_lshl_add_u64 v[82:83], v[82:83], 0, s[6:7]
	s_cmpk_lt_i32 s11, 0x4000
	s_cbranch_scc1 .LBB0_787
